# latent attention loop: back edge rotated out of the QK segment head (loop-back barrier becomes the loop head, exit path gets its own barrier copy)
# speedup vs baseline: 1.0033x; 1.0033x over previous
.LBB0_708:
	s_mov_b64 s[2:3], s[0:1]
	s_mov_b32 s4, s12
	s_mov_b32 s5, s13
	s_load_dwordx2 s[4:5], s[2:3], 0x70
	s_load_dwordx2 s[34:35], s[2:3], 0xe8
	s_lshl_b64 s[2:3], s[50:51], 2
	v_mov_b32_e32 v145, v220
	s_waitcnt lgkmcnt(0)
	s_add_u32 s4, s4, s2
	s_addc_u32 s5, s5, s3
	s_add_u32 s2, s34, 0x200000
	s_addc_u32 s3, s35, 0
	s_bfe_u32 s6, s9, 0x10002
	s_lshl_b32 s10, s6, 12
	s_or_b32 s11, s10, 0x2000
	s_lshl_b32 s10, s9, 5
	s_lshl_b32 s6, s6, 20
	s_and_b32 s7, s9, 3
	s_and_b32 s22, s10, 0xf00
	s_add_i32 s6, s6, s8
	s_and_b32 s16, s9, 0xffffff80
	s_or_b32 s10, s11, s22
	s_lshl_b32 s6, s6, 1
	s_lshl_b32 s15, s7, 8
	s_add_u32 s6, s34, s6
	s_addc_u32 s18, s35, 0
	s_add_u32 s20, s6, s15
	s_addc_u32 s21, s18, 0
	s_add_u32 s48, s20, 0x600000
	s_addc_u32 s49, s21, 0
	s_add_u32 s56, s20, 0xa00000
	s_addc_u32 s57, s21, 0
	s_lshl_b32 s6, s11, 10
	s_add_u32 s6, s34, s6
	s_addc_u32 s11, s35, 0
	s_add_u32 s6, s6, s15
	s_addc_u32 s11, s11, 0
	s_add_u32 s36, s6, 0x68600000
	s_addc_u32 s43, s11, 0
	s_add_u32 s44, s6, 0x69600000
	s_addc_u32 s52, s11, 0
	s_mul_i32 s6, s10, 0x4800
	s_add_u32 s6, s34, s6
	s_addc_u32 s15, s35, 0
	s_add_u32 s11, s6, 0x2e600000
	s_addc_u32 s15, s15, 0
	s_lshl_b32 s6, s7, 9
	s_add_i32 s6, s6, s16
	v_ashrrev_i32_e32 v136, 4, v145
	s_ashr_i32 s7, s6, 31
	v_add_u32_e32 v138, 32, v136
	s_lshl_b64 s[6:7], s[6:7], 1
	v_lshlrev_b32_e32 v18, 3, v145
	v_ashrrev_i32_e32 v137, 31, v136
	v_ashrrev_i32_e32 v139, 31, v138
	s_add_u32 s18, s11, s6
	v_ashrrev_i32_e32 v228, 6, v145
	v_and_b32_e32 v144, 0x78, v18
	v_lshlrev_b64 v[132:133], 10, v[136:137]
	v_lshlrev_b64 v[134:135], 10, v[138:139]
	s_addc_u32 s19, s15, s7
	v_and_b32_e32 v227, 31, v145
	v_lshlrev_b32_e32 v188, 1, v144
	v_lshl_add_u64 v[0:1], s[56:57], 0, v[132:133]
	v_mov_b32_e32 v189, v177
	v_lshl_add_u64 v[2:3], s[56:57], 0, v[134:135]
	v_lshlrev_b32_e32 v229, 5, v228
	v_bfe_u32 v226, v145, 5, 1
	v_lshl_add_u64 v[0:1], v[0:1], 0, v[188:189]
	v_lshl_add_u64 v[2:3], v[2:3], 0, v[188:189]
	v_or_b32_e32 v19, v229, v227
	v_mov_b64_e32 v[16:17], s[18:19]
	global_load_dwordx4 v[8:11], v[0:1], off
	global_load_dwordx4 v[4:7], v[2:3], off
	v_lshl_add_u64 v[0:1], s[48:49], 0, v[132:133]
	v_lshl_add_u64 v[2:3], s[48:49], 0, v[134:135]
	v_mad_i64_i32 v[16:17], s[18:19], v19, s45, v[16:17]
	v_lshlrev_b32_e32 v190, 4, v226
	v_mov_b32_e32 v191, v177
	v_lshl_add_u64 v[0:1], v[0:1], 0, v[188:189]
	v_lshl_add_u64 v[2:3], v[2:3], 0, v[188:189]
	v_lshl_add_u64 v[16:17], v[16:17], 0, v[190:191]
	global_load_dwordx4 v[12:15], v[0:1], off
	s_nop 0
	global_load_dwordx4 v[0:3], v[2:3], off
	s_barrier
	global_load_dwordx4 v[162:165], v[16:17], off offset:160
	global_load_dwordx4 v[166:169], v[16:17], off offset:224
	v_and_b32_e32 v20, 32, v145
	global_load_dwordx4 v[154:157], v20, s[4:5] offset:464
	global_load_dwordx4 v[32:35], v20, s[4:5] offset:336
	global_load_dwordx4 v[178:181], v[16:17], off offset:128
	global_load_dwordx4 v[182:185], v[16:17], off offset:192
	global_load_dwordx4 v[44:47], v20, s[4:5] offset:320
	global_load_dwordx4 v[192:195], v20, s[4:5] offset:448
	global_load_dwordx4 v[120:123], v[16:17], off
	global_load_dwordx4 v[128:131], v[16:17], off offset:32
	global_load_dwordx4 v[200:203], v20, s[4:5] offset:400
	global_load_dwordx4 v[80:83], v20, s[4:5] offset:272
	global_load_dwordx4 v[210:213], v20, s[4:5] offset:384
	global_load_dwordx4 v[88:91], v20, s[4:5] offset:256
	global_load_dwordx4 v[116:119], v[16:17], off offset:64
	global_load_dwordx4 v[232:235], v[16:17], off offset:96
	global_load_dwordx4 v[108:111], v20, s[4:5]
	global_load_dwordx4 v[104:107], v20, s[4:5] offset:16
	global_load_dwordx4 v[100:103], v20, s[4:5] offset:64
	global_load_dwordx4 v[96:99], v20, s[4:5] offset:80
	global_load_dwordx4 v[112:115], v20, s[4:5] offset:128
	global_load_dwordx4 v[124:127], v20, s[4:5] offset:144
	global_load_dwordx4 v[236:239], v20, s[4:5] offset:192
	global_load_dwordx4 v[240:243], v20, s[4:5] offset:208
	v_and_b32_e32 v21, 0xfffff0, v136
	v_lshlrev_b32_e32 v22, 1, v136
	v_and_or_b32 v21, v22, 8, v21
	v_lshrrev_b32_e32 v22, 1, v136
	v_and_b32_e32 v23, 3, v136
	v_and_or_b32 v22, v22, 4, v23
	v_and_b32_e32 v23, 0xfffff0, v138
	v_lshlrev_b32_e32 v24, 1, v138
	v_and_or_b32 v23, v24, 8, v23
	v_lshrrev_b32_e32 v21, 1, v21
	v_bfe_u32 v18, v18, 5, 2
	v_lshrrev_b32_e32 v23, 1, v23
	v_or_b32_e32 v21, v21, v18
	v_or_b32_e32 v18, v23, v18
	v_lshlrev_b32_e32 v21, 9, v21
	v_lshlrev_b32_e32 v22, 6, v22
	v_lshlrev_b32_e32 v18, 9, v18
	v_and_b32_e32 v16, 48, v188
	v_or3_b32 v191, v18, v22, v16
	v_or3_b32 v231, v21, v22, v16
	v_or_b32_e32 v16, s22, v227
	v_add_u32_e32 v16, v16, v229
	v_ashrrev_i32_e32 v16, 1, v16
	v_and_b32_e32 v16, 0xffffffe0, v16
	v_ashrrev_i32_e32 v17, 31, v16
	v_lshl_add_u64 v[16:17], v[16:17], 3, s[2:3]
	v_lshlrev_b32_e32 v176, 6, v226
	v_lshl_add_u64 v[16:17], v[16:17], 0, v[176:177]
	global_load_dwordx4 v[68:71], v[16:17], off offset:48
	global_load_dwordx4 v[76:79], v[16:17], off offset:32
	global_load_dwordx4 v[84:87], v[16:17], off offset:16
	global_load_dwordx4 v[92:95], v[16:17], off
	global_load_dwordx4 v[48:51], v[16:17], off offset:176
	global_load_dwordx4 v[56:59], v[16:17], off offset:160
	global_load_dwordx4 v[64:67], v[16:17], off offset:144
	global_load_dwordx4 v[72:75], v[16:17], off offset:128
	v_lshlrev_b32_e32 v16, 8, v19
	v_and_b32_e32 v16, 0x3f00, v16
	v_mov_b32_e32 v17, v177
	v_lshl_add_u64 v[16:17], s[2:3], 0, v[16:17]
	v_lshl_add_u64 v[36:37], v[16:17], 0, v[176:177]
	global_load_dwordx4 v[28:31], v[36:37], off offset:48
	global_load_dwordx4 v[40:43], v[36:37], off offset:32
	global_load_dwordx4 v[52:55], v[36:37], off offset:16
	global_load_dwordx4 v[60:63], v[36:37], off
	global_load_dwordx4 v[16:19], v[36:37], off offset:176
	global_load_dwordx4 v[20:23], v[36:37], off offset:160
	global_load_dwordx4 v[24:27], v[36:37], off offset:144
	s_nop 0
	global_load_dwordx4 v[36:39], v[36:37], off offset:128
	v_lshlrev_b32_e32 v230, 4, v145
	s_add_i32 s2, 0, 0x10000
	s_cmp_lg_u32 0, -1
	s_cselect_b32 s4, 0, 0
	s_mov_b32 s16, s17
	s_mov_b32 s18, s17
	s_mov_b32 s19, s17
	s_mov_b32 s24, s17
	s_mov_b32 s25, s17
	s_mov_b32 s26, s17
	s_mov_b32 s27, s17
	s_mov_b32 s28, s17
	s_mov_b32 s29, s17
	s_mov_b32 s30, s17
	s_mov_b32 s31, s17
	s_mov_b32 s85, 4
	v_lshlrev_b32_e32 v176, 1, v144
	s_waitcnt vmcnt(31)
	v_lshlrev_b32_e32 v225, 16, v123
	v_mov_b32_e32 v146, v156
	v_mov_b32_e32 v152, v154
	v_lshlrev_b32_e32 v141, 16, v165
	v_lshlrev_b32_e32 v140, 16, v169
	v_and_b32_e32 v142, 0xffff0000, v169
	v_lshlrev_b32_e32 v154, 16, v167
	v_and_b32_e32 v156, 0xffff0000, v167
	v_lshlrev_b32_e32 v167, 16, v181
	v_and_b32_e32 v169, 0xffff0000, v181
	s_waitcnt vmcnt(21)
	v_mov_b32_e32 v181, v102
	s_waitcnt vmcnt(17)
	v_mov_b32_e32 v102, v239
	v_lshlrev_b32_e32 v239, 16, v120
	v_and_b32_e32 v143, 0xffff0000, v165
	v_mov_b32_e32 v165, v44
	v_mov_b32_e32 v44, v193
	v_lshlrev_b32_e32 v175, 16, v180
	v_and_b32_e32 v193, 0xffff0000, v180
	s_waitcnt vmcnt(16)
	v_mov_b32_e32 v218, v240
	v_mov_b32_e32 v219, v96
	v_mov_b32_e32 v96, v241
	v_mov_b32_e32 v180, v238
	v_and_b32_e32 v241, 0xffff0000, v120
	v_lshlrev_b32_e32 v238, 16, v116
	v_and_b32_e32 v240, 0xffff0000, v116
	v_mul_f32_e32 v116, v239, v239
	v_mov_b32_e32 v170, v202
	v_mov_b32_e32 v202, v212
	v_mov_b32_e32 v208, v210
	v_lshlrev_b32_e32 v210, 16, v235
	v_and_b32_e32 v212, 0xffff0000, v235
	v_mov_b32_e32 v235, v104
	v_mov_b32_e32 v104, v125
	v_lshlrev_b32_e32 v125, 16, v121
	v_fmac_f32_e32 v116, v241, v241
	v_and_b32_e32 v121, 0xffff0000, v121
	v_fmac_f32_e32 v116, v125, v125
	v_lshlrev_b32_e32 v205, 16, v178
	v_lshlrev_b32_e32 v204, 16, v182
	v_and_b32_e32 v207, 0xffff0000, v178
	v_and_b32_e32 v206, 0xffff0000, v182
	v_lshlrev_b32_e32 v178, 16, v233
	v_and_b32_e32 v182, 0xffff0000, v233
	v_mov_b32_e32 v233, v106
	v_mov_b32_e32 v106, v127
	v_lshlrev_b32_e32 v127, 16, v122
	v_fmac_f32_e32 v116, v121, v121
	v_mov_b32_e32 v187, v100
	v_mov_b32_e32 v100, v237
	v_and_b32_e32 v237, 0xffff0000, v122
	v_fmac_f32_e32 v116, v127, v127
	v_fmac_f32_e32 v116, v237, v237
	v_and_b32_e32 v123, 0xffff0000, v123
	v_fmac_f32_e32 v116, v225, v225
	v_mov_b32_e32 v147, v34
	v_mov_b32_e32 v34, v157
	v_lshlrev_b32_e32 v148, 16, v168
	v_mov_b32_e32 v153, v32
	v_and_b32_e32 v150, 0xffff0000, v168
	v_mov_b32_e32 v32, v155
	v_lshlrev_b32_e32 v155, 16, v163
	v_and_b32_e32 v157, 0xffff0000, v163
	v_lshlrev_b32_e32 v161, 16, v162
	v_lshlrev_b32_e32 v160, 16, v166
	v_and_b32_e32 v163, 0xffff0000, v162
	v_and_b32_e32 v162, 0xffff0000, v166
	v_lshlrev_b32_e32 v166, 16, v185
	v_and_b32_e32 v168, 0xffff0000, v185
	v_lshlrev_b32_e32 v185, 16, v128
	v_fmac_f32_e32 v116, v123, v123
	v_mov_b32_e32 v158, v194
	v_mov_b32_e32 v159, v46
	v_mov_b32_e32 v46, v195
	v_mov_b32_e32 v194, v200
	v_mov_b32_e32 v195, v80
	v_mov_b32_e32 v80, v201
	v_lshlrev_b32_e32 v197, 16, v179
	v_lshlrev_b32_e32 v196, 16, v183
	v_and_b32_e32 v201, 0xffff0000, v179
	v_and_b32_e32 v200, 0xffff0000, v183
	v_lshlrev_b32_e32 v179, 16, v129
	v_and_b32_e32 v183, 0xffff0000, v129
	v_and_b32_e32 v129, 0xffff0000, v128
	v_fmac_f32_e32 v116, v185, v185
	v_fmac_f32_e32 v116, v129, v129
	v_fmac_f32_e32 v116, v179, v179
	v_lshlrev_b32_e32 v217, 16, v130
	v_fmac_f32_e32 v116, v183, v183
	v_mov_b32_e32 v171, v82
	v_mov_b32_e32 v82, v203
	v_mov_b32_e32 v203, v90
	v_mov_b32_e32 v90, v213
	v_mov_b32_e32 v209, v88
	v_mov_b32_e32 v88, v211
	v_lshlrev_b32_e32 v211, 16, v131
	v_and_b32_e32 v213, 0xffff0000, v131
	v_and_b32_e32 v131, 0xffff0000, v130
	v_fmac_f32_e32 v116, v217, v217
	v_fmac_f32_e32 v116, v131, v131
	v_fmac_f32_e32 v116, v211, v211
	v_fmac_f32_e32 v116, v213, v213
	v_lshlrev_b32_e32 v216, 16, v234
	v_and_b32_e32 v130, 0xffff0000, v234
	v_mov_b32_e32 v234, v124
	v_lshlrev_b32_e32 v124, 16, v117
	v_and_b32_e32 v120, 0xffff0000, v117
	v_pk_fma_f32 v[116:117], v[238:239], v[238:239], v[116:117] op_sel_hi:[1,1,0]
	v_lshlrev_b32_e32 v149, 16, v164
	v_pk_fma_f32 v[116:117], v[240:241], v[240:241], v[116:117]
	v_and_b32_e32 v151, 0xffff0000, v164
	v_pk_fma_f32 v[116:117], v[124:125], v[124:125], v[116:117]
	v_mov_b32_e32 v164, v192
	v_lshlrev_b32_e32 v174, 16, v184
	v_and_b32_e32 v192, 0xffff0000, v184
	v_lshlrev_b32_e32 v184, 16, v232
	v_and_b32_e32 v128, 0xffff0000, v232
	v_mov_b32_e32 v232, v126
	v_lshlrev_b32_e32 v126, 16, v118
	v_pk_fma_f32 v[116:117], v[120:121], v[120:121], v[116:117]
	v_mov_b32_e32 v186, v236
	v_and_b32_e32 v236, 0xffff0000, v118
	v_pk_fma_f32 v[116:117], v[126:127], v[126:127], v[116:117]
	v_lshlrev_b32_e32 v224, 16, v119
	v_pk_fma_f32 v[116:117], v[236:237], v[236:237], v[116:117]
	v_and_b32_e32 v122, 0xffff0000, v119
	v_pk_fma_f32 v[116:117], v[224:225], v[224:225], v[116:117]
	v_mul_f32_e32 v118, v205, v205
	v_pk_fma_f32 v[116:117], v[122:123], v[122:123], v[116:117]
	v_mov_b32_e32 v214, v242
	v_pk_fma_f32 v[116:117], v[184:185], v[184:185], v[116:117]
	v_mov_b32_e32 v215, v98
	v_pk_fma_f32 v[116:117], v[128:129], v[128:129], v[116:117]
	v_mov_b32_e32 v98, v243
	v_pk_fma_f32 v[116:117], v[178:179], v[178:179], v[116:117]
	v_mov_b32_e32 v242, v156
	v_pk_fma_f32 v[116:117], v[182:183], v[182:183], v[116:117]
	v_mov_b32_e32 v243, v154
	v_pk_fma_f32 v[116:117], v[216:217], v[216:217], v[116:117]
	v_mov_b32_e32 v198, v150
	v_pk_fma_f32 v[116:117], v[130:131], v[130:131], v[116:117]
	v_mov_b32_e32 v199, v148
	v_pk_fma_f32 v[116:117], v[210:211], v[210:211], v[116:117]
	v_mov_b32_e32 v172, v142
	v_pk_fma_f32 v[116:117], v[212:213], v[212:213], v[116:117]
	v_mov_b32_e32 v173, v140
	v_pk_add_f32 v[116:117], v[118:119], v[116:117] op_sel_hi:[0,1]
	v_mul_f32_e32 v118, v207, v207
	v_pk_add_f32 v[116:117], v[118:119], v[116:117] op_sel_hi:[0,1]
	v_mul_f32_e32 v118, v197, v197
	v_pk_add_f32 v[116:117], v[118:119], v[116:117] op_sel_hi:[0,1]
	v_mul_f32_e32 v118, v201, v201
	v_pk_add_f32 v[116:117], v[118:119], v[116:117] op_sel_hi:[0,1]
	v_mul_f32_e32 v118, v175, v175
	v_pk_add_f32 v[116:117], v[118:119], v[116:117] op_sel_hi:[0,1]
	v_mul_f32_e32 v118, v193, v193
	v_pk_add_f32 v[116:117], v[118:119], v[116:117] op_sel_hi:[0,1]
	v_mul_f32_e32 v118, v167, v167
	v_pk_add_f32 v[116:117], v[118:119], v[116:117] op_sel_hi:[0,1]
	v_mul_f32_e32 v118, v169, v169
	v_pk_add_f32 v[116:117], v[118:119], v[116:117] op_sel_hi:[0,1]
	v_mul_f32_e32 v118, v161, v161
	v_pk_add_f32 v[116:117], v[118:119], v[116:117] op_sel_hi:[0,1]
	v_mul_f32_e32 v118, v163, v163
	v_pk_add_f32 v[116:117], v[118:119], v[116:117] op_sel_hi:[0,1]
	v_mul_f32_e32 v118, v155, v155
	v_pk_add_f32 v[116:117], v[118:119], v[116:117] op_sel_hi:[0,1]
	v_mul_f32_e32 v118, v157, v157
	v_pk_add_f32 v[116:117], v[118:119], v[116:117] op_sel_hi:[0,1]
	v_mul_f32_e32 v118, v149, v149
	v_pk_add_f32 v[116:117], v[118:119], v[116:117] op_sel_hi:[0,1]
	v_mul_f32_e32 v118, v151, v151
	v_pk_add_f32 v[116:117], v[118:119], v[116:117] op_sel_hi:[0,1]
	v_mul_f32_e32 v118, v141, v141
	v_pk_add_f32 v[116:117], v[118:119], v[116:117] op_sel_hi:[0,1]
	v_mul_f32_e32 v118, v143, v143
	v_pk_add_f32 v[116:117], v[118:119], v[116:117] op_sel_hi:[0,1]
	v_pk_fma_f32 v[116:117], v[204:205], v[204:205], v[116:117]
	v_mul_f32_e32 v118, v154, v154
	v_pk_fma_f32 v[116:117], v[206:207], v[206:207], v[116:117]
	s_nop 0
	v_pk_fma_f32 v[116:117], v[196:197], v[196:197], v[116:117]
	s_nop 0
	v_pk_fma_f32 v[116:117], v[200:201], v[200:201], v[116:117]
	s_nop 0
	v_pk_fma_f32 v[116:117], v[174:175], v[174:175], v[116:117]
	s_nop 0
	v_pk_fma_f32 v[116:117], v[192:193], v[192:193], v[116:117]
	s_nop 0
	v_pk_fma_f32 v[116:117], v[166:167], v[166:167], v[116:117]
	s_nop 0
	v_pk_fma_f32 v[116:117], v[168:169], v[168:169], v[116:117]
	s_nop 0
	v_pk_fma_f32 v[116:117], v[160:161], v[160:161], v[116:117]
	s_nop 0
	v_pk_fma_f32 v[116:117], v[162:163], v[162:163], v[116:117]
	s_nop 0
	v_pk_add_f32 v[116:117], v[118:119], v[116:117] op_sel_hi:[0,1]
	v_mov_b32_e32 v119, v110
	v_pk_fma_f32 v[116:117], v[242:243], v[242:243], v[116:117]
	v_mul_f32_e32 v110, v148, v148
	v_pk_add_f32 v[116:117], v[110:111], v[116:117] op_sel_hi:[0,1]
	v_pk_fma_f32 v[116:117], v[198:199], v[198:199], v[116:117]
	v_mul_f32_e32 v110, v140, v140
	v_pk_add_f32 v[116:117], v[110:111], v[116:117] op_sel_hi:[0,1]
	v_pk_fma_f32 v[116:117], v[172:173], v[172:173], v[116:117]
	v_mov_b32_e32 v118, v114
	v_mov_b32_e32 v110, v116
	s_nop 1
	v_permlane32_swap_b32_e32 v116, v110
	v_add_f32_e32 v110, v116, v110
	v_fmamk_f32 v110, v110, 0x3c000000, v221
	v_mul_f32_e32 v114, 0x4b800000, v110
	v_cmp_gt_f32_e32 vcc, s42, v110
	s_nop 1
	v_cndmask_b32_e32 v110, v110, v114, vcc
	v_rsq_f32_e32 v116, v110
	v_mov_b32_e32 v110, v115
	v_mov_b32_e32 v115, v108
	v_mov_b32_e32 v114, v112
	v_mul_f32_e32 v108, 0x45800000, v116
	v_cndmask_b32_e32 v112, v116, v108, vcc
	v_pk_mul_f32 v[114:115], v[114:115], v[112:113] op_sel_hi:[1,0]
	v_mov_b32_e32 v108, v113
	v_pk_mul_f32 v[114:115], v[114:115], v[238:239]
	v_pk_mul_f32 v[116:117], v[234:235], v[112:113] op_sel_hi:[1,0]
	v_pk_mul_f32 v[108:109], v[108:109], v[112:113] op_sel_hi:[1,0]
	v_pk_mul_f32 v[118:119], v[118:119], v[112:113] op_sel_hi:[1,0]
	v_pk_mul_f32 v[110:111], v[110:111], v[112:113] op_sel_hi:[1,0]
	v_pk_mul_f32 v[106:107], v[106:107], v[112:113] op_sel_hi:[1,0]
	v_pk_mul_f32 v[100:101], v[100:101], v[112:113] op_sel_hi:[1,0]
	v_pk_mul_f32 v[96:97], v[96:97], v[112:113] op_sel_hi:[1,0]
	v_pk_mul_f32 v[172:173], v[112:113], v[194:195] op_sel_hi:[0,1]
	v_pk_mul_f32 v[32:33], v[112:113], v[32:33] op_sel_hi:[0,1]
	v_pk_mul_f32 v[116:117], v[116:117], v[126:127]
	v_pk_mul_f32 v[108:109], v[108:109], v[240:241]
	v_pk_mul_f32 v[104:105], v[104:105], v[112:113] op_sel_hi:[1,0]
	v_pk_mul_f32 v[118:119], v[118:119], v[124:125]
	v_pk_mul_f32 v[124:125], v[232:233], v[112:113] op_sel_hi:[1,0]
	v_pk_mul_f32 v[110:111], v[110:111], v[120:121]
	v_pk_mul_f32 v[106:107], v[106:107], v[122:123]
	v_pk_mul_f32 v[120:121], v[186:187], v[112:113] op_sel_hi:[1,0]
	v_pk_mul_f32 v[122:123], v[218:219], v[112:113] op_sel_hi:[1,0]
	v_pk_mul_f32 v[100:101], v[100:101], v[128:129]
	v_pk_mul_f32 v[96:97], v[96:97], v[130:131]
	v_pk_mul_f32 v[126:127], v[180:181], v[112:113] op_sel_hi:[1,0]
	v_pk_mul_f32 v[128:129], v[214:215], v[112:113] op_sel_hi:[1,0]
	v_pk_mul_f32 v[102:103], v[102:103], v[112:113] op_sel_hi:[1,0]
	v_pk_mul_f32 v[98:99], v[98:99], v[112:113] op_sel_hi:[1,0]
	v_pk_mul_f32 v[130:131], v[112:113], v[208:209] op_sel_hi:[0,1]
	v_pk_mul_f32 v[172:173], v[172:173], v[174:175]
	v_pk_mul_f32 v[88:89], v[112:113], v[88:89] op_sel_hi:[0,1]
	v_pk_mul_f32 v[80:81], v[112:113], v[80:81] op_sel_hi:[0,1]
	v_pk_mul_f32 v[174:175], v[112:113], v[202:203] op_sel_hi:[0,1]
	v_pk_mul_f32 v[170:171], v[112:113], v[170:171] op_sel_hi:[0,1]
	v_pk_mul_f32 v[90:91], v[112:113], v[90:91] op_sel_hi:[0,1]
	v_pk_mul_f32 v[82:83], v[112:113], v[82:83] op_sel_hi:[0,1]
	v_pk_mul_f32 v[164:165], v[112:113], v[164:165] op_sel_hi:[0,1]
	v_pk_mul_f32 v[152:153], v[112:113], v[152:153] op_sel_hi:[0,1]
	v_pk_mul_f32 v[44:45], v[112:113], v[44:45] op_sel_hi:[0,1]
	v_pk_mul_f32 v[32:33], v[32:33], v[150:151]
	v_pk_mul_f32 v[150:151], v[112:113], v[158:159] op_sel_hi:[0,1]
	v_pk_mul_f32 v[146:147], v[112:113], v[146:147] op_sel_hi:[0,1]
	v_pk_mul_f32 v[46:47], v[112:113], v[46:47] op_sel_hi:[0,1]
	v_pk_mul_f32 v[34:35], v[112:113], v[34:35] op_sel_hi:[0,1]
	s_waitcnt vmcnt(12)
	v_pk_mul_f32 v[112:113], v[114:115], v[92:93] op_sel:[1,0] op_sel_hi:[0,1]
	v_pk_mul_f32 v[92:93], v[114:115], v[92:93]
	v_sub_f32_e32 v112, v112, v113
	v_add_f32_e32 v113, v93, v92
	v_pk_mul_f32 v[92:93], v[108:109], v[94:95] op_sel:[1,0] op_sel_hi:[0,1]
	v_sub_f32_e32 v114, v92, v93
	v_pk_mul_f32 v[92:93], v[108:109], v[94:95]
	v_pk_mul_f32 v[104:105], v[104:105], v[236:237]
	v_add_f32_e32 v94, v93, v92
	v_pk_mul_f32 v[92:93], v[118:119], v[84:85] op_sel:[1,0] op_sel_hi:[0,1]
	v_pk_mul_f32 v[84:85], v[118:119], v[84:85]
	v_sub_f32_e32 v92, v92, v93
	v_add_f32_e32 v93, v85, v84
	v_pk_mul_f32 v[84:85], v[110:111], v[86:87] op_sel:[1,0] op_sel_hi:[0,1]
	v_sub_f32_e32 v95, v84, v85
	v_pk_mul_f32 v[84:85], v[110:111], v[86:87]
	v_pk_mul_f32 v[124:125], v[124:125], v[224:225]
	v_add_f32_e32 v86, v85, v84
	v_pk_mul_f32 v[84:85], v[116:117], v[76:77] op_sel:[1,0] op_sel_hi:[0,1]
	v_pk_mul_f32 v[76:77], v[116:117], v[76:77]
	v_sub_f32_e32 v84, v84, v85
	v_add_f32_e32 v85, v77, v76
	v_pk_mul_f32 v[76:77], v[104:105], v[78:79] op_sel:[1,0] op_sel_hi:[0,1]
	v_sub_f32_e32 v87, v76, v77
	v_pk_mul_f32 v[76:77], v[104:105], v[78:79]
	v_pk_mul_f32 v[120:121], v[120:121], v[184:185]
	v_add_f32_e32 v78, v77, v76
	v_pk_mul_f32 v[76:77], v[124:125], v[68:69] op_sel:[1,0] op_sel_hi:[0,1]
	v_pk_mul_f32 v[68:69], v[124:125], v[68:69]
	v_sub_f32_e32 v76, v76, v77
	v_add_f32_e32 v77, v69, v68
	v_pk_mul_f32 v[68:69], v[106:107], v[70:71] op_sel:[1,0] op_sel_hi:[0,1]
	v_sub_f32_e32 v79, v68, v69
	v_pk_mul_f32 v[68:69], v[106:107], v[70:71]
	v_pk_mul_f32 v[126:127], v[126:127], v[178:179]
	v_add_f32_e32 v70, v69, v68
	s_waitcnt vmcnt(8)
	v_pk_mul_f32 v[68:69], v[120:121], v[72:73] op_sel:[1,0] op_sel_hi:[0,1]
	v_sub_f32_e32 v71, v68, v69
	v_pk_mul_f32 v[68:69], v[120:121], v[72:73]
	v_pk_mul_f32 v[102:103], v[102:103], v[182:183]
	v_add_f32_e32 v72, v69, v68
	v_pk_mul_f32 v[68:69], v[100:101], v[74:75] op_sel:[1,0] op_sel_hi:[0,1]
	v_sub_f32_e32 v73, v68, v69
	v_pk_mul_f32 v[68:69], v[100:101], v[74:75]
	v_pk_mul_f32 v[122:123], v[122:123], v[216:217]
	v_add_f32_e32 v74, v69, v68
	v_pk_mul_f32 v[68:69], v[126:127], v[64:65] op_sel:[1,0] op_sel_hi:[0,1]
	v_pk_mul_f32 v[64:65], v[126:127], v[64:65]
	v_sub_f32_e32 v68, v68, v69
	v_add_f32_e32 v69, v65, v64
	v_pk_mul_f32 v[64:65], v[102:103], v[66:67] op_sel:[1,0] op_sel_hi:[0,1]
	v_sub_f32_e32 v75, v64, v65
	v_pk_mul_f32 v[64:65], v[102:103], v[66:67]
	v_pk_mul_f32 v[128:129], v[128:129], v[210:211]
	v_add_f32_e32 v66, v65, v64
	v_pk_mul_f32 v[64:65], v[122:123], v[56:57] op_sel:[1,0] op_sel_hi:[0,1]
	v_pk_mul_f32 v[56:57], v[122:123], v[56:57]
	v_sub_f32_e32 v64, v64, v65
	v_add_f32_e32 v65, v57, v56
	v_pk_mul_f32 v[56:57], v[96:97], v[58:59] op_sel:[1,0] op_sel_hi:[0,1]
	v_sub_f32_e32 v67, v56, v57
	v_pk_mul_f32 v[56:57], v[96:97], v[58:59]
	v_pk_mul_f32 v[98:99], v[98:99], v[212:213]
	v_add_f32_e32 v58, v57, v56
	v_pk_mul_f32 v[56:57], v[128:129], v[48:49] op_sel:[1,0] op_sel_hi:[0,1]
	v_pk_mul_f32 v[48:49], v[128:129], v[48:49]
	v_sub_f32_e32 v56, v56, v57
	v_add_f32_e32 v57, v49, v48
	v_pk_mul_f32 v[48:49], v[98:99], v[50:51] op_sel:[1,0] op_sel_hi:[0,1]
	v_pk_mul_f32 v[130:131], v[130:131], v[204:205]
	v_sub_f32_e32 v59, v48, v49
	v_pk_mul_f32 v[48:49], v[98:99], v[50:51]
	v_pk_mul_f32 v[88:89], v[88:89], v[206:207]
	v_add_f32_e32 v50, v49, v48
	s_waitcnt vmcnt(4)
	v_pk_mul_f32 v[48:49], v[130:131], v[60:61] op_sel:[1,0] op_sel_hi:[0,1]
	v_sub_f32_e32 v51, v48, v49
	v_pk_mul_f32 v[48:49], v[130:131], v[60:61]
	v_pk_mul_f32 v[174:175], v[174:175], v[196:197]
	v_add_f32_e32 v60, v49, v48
	v_pk_mul_f32 v[48:49], v[88:89], v[62:63] op_sel:[1,0] op_sel_hi:[0,1]
	v_sub_f32_e32 v61, v48, v49
	v_pk_mul_f32 v[48:49], v[88:89], v[62:63]
	v_pk_mul_f32 v[90:91], v[90:91], v[200:201]
	v_add_f32_e32 v62, v49, v48
	v_pk_mul_f32 v[48:49], v[174:175], v[52:53] op_sel:[1,0] op_sel_hi:[0,1]
	v_sub_f32_e32 v63, v48, v49
	v_pk_mul_f32 v[48:49], v[174:175], v[52:53]
	v_pk_mul_f32 v[80:81], v[80:81], v[192:193]
	v_add_f32_e32 v52, v49, v48
	v_pk_mul_f32 v[48:49], v[90:91], v[54:55] op_sel:[1,0] op_sel_hi:[0,1]
	v_sub_f32_e32 v53, v48, v49
	v_pk_mul_f32 v[48:49], v[90:91], v[54:55]
	v_pk_mul_f32 v[166:167], v[170:171], v[166:167]
	v_add_f32_e32 v54, v49, v48
	v_pk_mul_f32 v[48:49], v[172:173], v[40:41] op_sel:[1,0] op_sel_hi:[0,1]
	v_pk_mul_f32 v[40:41], v[172:173], v[40:41]
	v_sub_f32_e32 v48, v48, v49
	v_add_f32_e32 v49, v41, v40
	v_pk_mul_f32 v[40:41], v[80:81], v[42:43] op_sel:[1,0] op_sel_hi:[0,1]
	v_sub_f32_e32 v55, v40, v41
	v_pk_mul_f32 v[40:41], v[80:81], v[42:43]
	v_pk_mul_f32 v[82:83], v[82:83], v[168:169]
	v_add_f32_e32 v42, v41, v40
	v_pk_mul_f32 v[40:41], v[166:167], v[28:29] op_sel:[1,0] op_sel_hi:[0,1]
	v_pk_mul_f32 v[28:29], v[166:167], v[28:29]
	v_sub_f32_e32 v40, v40, v41
	v_add_f32_e32 v41, v29, v28
	v_pk_mul_f32 v[28:29], v[82:83], v[30:31] op_sel:[1,0] op_sel_hi:[0,1]
	v_pk_mul_f32 v[160:161], v[164:165], v[160:161]
	v_sub_f32_e32 v43, v28, v29
	v_pk_mul_f32 v[28:29], v[82:83], v[30:31]
	v_pk_mul_f32 v[44:45], v[44:45], v[162:163]
	v_add_f32_e32 v30, v29, v28
	s_waitcnt vmcnt(0)
	v_pk_mul_f32 v[28:29], v[160:161], v[36:37] op_sel:[1,0] op_sel_hi:[0,1]
	v_sub_f32_e32 v31, v28, v29
	v_pk_mul_f32 v[28:29], v[160:161], v[36:37]
	v_pk_mul_f32 v[150:151], v[150:151], v[154:155]
	v_add_f32_e32 v36, v29, v28
	v_pk_mul_f32 v[28:29], v[44:45], v[38:39] op_sel:[1,0] op_sel_hi:[0,1]
	v_sub_f32_e32 v37, v28, v29
	v_pk_mul_f32 v[28:29], v[44:45], v[38:39]
	v_pk_mul_f32 v[46:47], v[46:47], v[156:157]
	v_add_f32_e32 v38, v29, v28
	v_pk_mul_f32 v[28:29], v[150:151], v[24:25] op_sel:[1,0] op_sel_hi:[0,1]
	v_pk_mul_f32 v[24:25], v[150:151], v[24:25]
	v_sub_f32_e32 v28, v28, v29
	v_add_f32_e32 v29, v25, v24
	v_pk_mul_f32 v[24:25], v[46:47], v[26:27] op_sel:[1,0] op_sel_hi:[0,1]
	v_pk_mul_f32 v[148:149], v[152:153], v[148:149]
	v_sub_f32_e32 v39, v24, v25
	v_pk_mul_f32 v[24:25], v[46:47], v[26:27]
	v_pk_mul_f32 v[140:141], v[146:147], v[140:141]
	v_add_f32_e32 v26, v25, v24
	v_pk_mul_f32 v[24:25], v[148:149], v[20:21] op_sel:[1,0] op_sel_hi:[0,1]
	v_pk_mul_f32 v[20:21], v[148:149], v[20:21]
	v_sub_f32_e32 v24, v24, v25
	v_add_f32_e32 v25, v21, v20
	v_pk_mul_f32 v[20:21], v[32:33], v[22:23] op_sel:[1,0] op_sel_hi:[0,1]
	v_sub_f32_e32 v27, v20, v21
	v_pk_mul_f32 v[20:21], v[32:33], v[22:23]
	v_pk_mul_f32 v[34:35], v[34:35], v[142:143]
	v_add_f32_e32 v22, v21, v20
	v_pk_mul_f32 v[20:21], v[140:141], v[16:17] op_sel:[1,0] op_sel_hi:[0,1]
	v_pk_mul_f32 v[16:17], v[140:141], v[16:17]
	v_sub_f32_e32 v20, v20, v21
	v_add_f32_e32 v21, v17, v16
	v_pk_mul_f32 v[16:17], v[34:35], v[18:19] op_sel:[1,0] op_sel_hi:[0,1]
	v_sub_f32_e32 v23, v16, v17
	v_pk_mul_f32 v[16:17], v[34:35], v[18:19]
	v_add_u32_e32 v200, 0, v231
	v_add_u32_e32 v201, 0, v191
	v_add_f32_e32 v16, v17, v16
	v_cvt_pk_bf16_f32 v124, v112, v114
	v_cvt_pk_bf16_f32 v125, v92, v95
	v_cvt_pk_bf16_f32 v126, v84, v87
	v_cvt_pk_bf16_f32 v127, v76, v79
	v_cvt_pk_bf16_f32 v120, v71, v73
	v_cvt_pk_bf16_f32 v121, v68, v75
	v_cvt_pk_bf16_f32 v122, v64, v67
	v_cvt_pk_bf16_f32 v123, v56, v59
	v_cvt_pk_bf16_f32 v116, v113, v94
	v_cvt_pk_bf16_f32 v117, v93, v86
	v_cvt_pk_bf16_f32 v118, v85, v78
	v_cvt_pk_bf16_f32 v119, v77, v70
	v_cvt_pk_bf16_f32 v112, v72, v74
	v_cvt_pk_bf16_f32 v113, v69, v66
	v_cvt_pk_bf16_f32 v114, v65, v58
	v_cvt_pk_bf16_f32 v115, v57, v50
	v_cvt_pk_bf16_f32 v108, v51, v61
	v_cvt_pk_bf16_f32 v109, v63, v53
	v_cvt_pk_bf16_f32 v110, v48, v55
	v_cvt_pk_bf16_f32 v111, v40, v43
	v_cvt_pk_bf16_f32 v104, v31, v37
	v_cvt_pk_bf16_f32 v105, v28, v39
	v_cvt_pk_bf16_f32 v106, v24, v27
	v_cvt_pk_bf16_f32 v107, v20, v23
	v_cvt_pk_bf16_f32 v100, v60, v62
	v_cvt_pk_bf16_f32 v101, v52, v54
	v_cvt_pk_bf16_f32 v102, v49, v42
	v_cvt_pk_bf16_f32 v103, v41, v30
	v_cvt_pk_bf16_f32 v96, v36, v38
	v_cvt_pk_bf16_f32 v97, v29, v26
	v_cvt_pk_bf16_f32 v98, v25, v22
	v_cvt_pk_bf16_f32 v99, v21, v16
	s_waitcnt vmcnt(0)
	ds_write_b128 v200, v[8:11]
	ds_write_b128 v201, v[4:7]
	v_lshlrev_b32_e32 v4, 8, v136
	v_and_b32_e32 v5, 0x70, v145
	v_bitop3_b32 v4, v188, v4, v5 bitop3:0xde
	v_add_u32_e32 v202, 0, v4
	v_lshlrev_b32_e32 v4, 8, v138
	v_bitop3_b32 v4, v188, v4, v5 bitop3:0xde
	v_add_u32_e32 v203, 0, v4
	v_lshlrev_b32_e32 v8, 8, v227
	v_and_b32_e32 v9, 0x70, v230
	ds_write_b128 v202, v[12:15] offset:32768
	ds_write_b128 v203, v[0:3] offset:32768
	v_bitop3_b32 v0, v190, v8, v9 bitop3:0xde
	v_add_u32_e32 v204, 0, v0
	s_waitcnt lgkmcnt(0)
	s_barrier
	ds_read_b128 v[0:3], v204 offset:32768
	ds_read_b128 v[4:7], v204 offset:40960
	s_waitcnt lgkmcnt(1)
	v_mfma_f32_32x32x16_bf16 v[32:47], v[0:3], v[124:127], 0
	v_or_b32_e32 v0, 32, v190
	v_bitop3_b32 v0, v0, v8, v9 bitop3:0xde
	v_add_u32_e32 v207, 0, v0
	v_and_b32_e32 v196, 63, v145
	v_lshlrev_b32_e32 v10, 3, v196
	v_and_b32_e32 v11, 0xc0, v230
	v_lshlrev_b64 v[64:65], 9, v[136:137]
	s_waitcnt lgkmcnt(0)
	v_mfma_f32_32x32x16_bf16 v[16:31], v[4:7], v[124:127], 0
	ds_read_b128 v[0:3], v207 offset:32768
	ds_read_b128 v[4:7], v207 offset:40960
	v_lshlrev_b64 v[66:67], 9, v[138:139]
	v_mov_b32_e32 v197, 0
	v_lshlrev_b64 v[192:193], 1, v[64:65]
	v_lshlrev_b64 v[194:195], 1, v[66:67]
	s_waitcnt lgkmcnt(1)
	v_mfma_f32_32x32x16_bf16 v[32:47], v[0:3], v[120:123], v[32:47]
	v_or_b32_e32 v0, 64, v190
	v_bitop3_b32 v0, v0, v8, v9 bitop3:0xde
	v_add_u32_e32 v209, 0, v0
	s_waitcnt lgkmcnt(0)
	v_mfma_f32_32x32x16_bf16 v[16:31], v[4:7], v[120:123], v[16:31]
	ds_read_b128 v[0:3], v209 offset:32768
	ds_read_b128 v[4:7], v209 offset:40960
	s_waitcnt lgkmcnt(1)
	v_mfma_f32_32x32x16_bf16 v[32:47], v[0:3], v[116:119], v[32:47]
	v_or_b32_e32 v0, 0x60, v190
	v_bitop3_b32 v0, v0, v8, v9 bitop3:0xde
	v_add_u32_e32 v205, 0, v0
	s_waitcnt lgkmcnt(0)
	v_mfma_f32_32x32x16_bf16 v[16:31], v[4:7], v[116:119], v[16:31]
	ds_read_b128 v[0:3], v205 offset:32768
	ds_read_b128 v[4:7], v205 offset:40960
	s_waitcnt lgkmcnt(1)
	v_mfma_f32_32x32x16_bf16 v[32:47], v[0:3], v[112:115], v[32:47]
	v_or_b32_e32 v0, 0x80, v190
	v_bitop3_b32 v0, v0, v8, v9 bitop3:0xde
	v_add_u32_e32 v206, 0, v0
	s_waitcnt lgkmcnt(0)
	v_mfma_f32_32x32x16_bf16 v[16:31], v[4:7], v[112:115], v[16:31]
	ds_read_b128 v[0:3], v206 offset:32768
	ds_read_b128 v[4:7], v206 offset:40960
	s_waitcnt lgkmcnt(1)
	v_mfma_f32_32x32x16_bf16 v[32:47], v[0:3], v[108:111], v[32:47]
	v_or_b32_e32 v0, 0xa0, v190
	v_bitop3_b32 v0, v0, v8, v9 bitop3:0xde
	v_add_u32_e32 v208, 0, v0
	s_waitcnt lgkmcnt(0)
	v_mfma_f32_32x32x16_bf16 v[16:31], v[4:7], v[108:111], v[16:31]
	ds_read_b128 v[0:3], v208 offset:32768
	ds_read_b128 v[4:7], v208 offset:40960
	s_waitcnt lgkmcnt(1)
	v_mfma_f32_32x32x16_bf16 v[32:47], v[0:3], v[104:107], v[32:47]
	v_or_b32_e32 v0, 0xc0, v190
	v_bitop3_b32 v0, v0, v8, v9 bitop3:0xde
	v_add_u32_e32 v210, 0, v0
	ds_read_b128 v[0:3], v210 offset:32768
	s_waitcnt lgkmcnt(1)
	v_mfma_f32_32x32x16_bf16 v[16:31], v[4:7], v[104:107], v[16:31]
	v_and_b32_e32 v4, 0x3fffffc0, v145
	v_lshl_add_u32 v191, v4, 2, s2
	ds_read_b128 v[4:7], v210 offset:40960
	s_waitcnt lgkmcnt(1)
	v_mfma_f32_32x32x16_bf16 v[32:47], v[0:3], v[100:103], v[32:47]
	v_or_b32_e32 v0, 0xe0, v190
	v_bitop3_b32 v0, v0, v8, v9 bitop3:0xde
	v_add_u32_e32 v211, 0, v0
	ds_read_b128 v[0:3], v211 offset:32768
	s_waitcnt lgkmcnt(1)
	v_mfma_f32_32x32x16_bf16 v[16:31], v[4:7], v[100:103], v[16:31]
	v_lshlrev_b32_e32 v5, 1, v145
	v_and_or_b32 v4, v10, 24, v11
	v_and_b32_e32 v5, 32, v5
	v_and_b32_e32 v6, 0x100, v10
	v_or3_b32 v69, v4, v5, v6
	ds_read_b128 v[4:7], v211 offset:40960
	v_add_u32_e32 v199, s4, v69
	s_waitcnt lgkmcnt(1)
	v_mfma_f32_32x32x16_bf16 v[32:47], v[0:3], v[96:99], v[32:47]
	s_waitcnt lgkmcnt(0)
	v_mfma_f32_32x32x16_bf16 v[16:31], v[4:7], v[96:99], v[16:31]
	s_nop 9
	v_max_f32_e32 v0, v33, v33
	v_max_f32_e32 v1, v32, v32
	v_max_f32_e32 v0, v1, v0
	v_max3_f32 v0, v0, v34, v35
	v_max3_f32 v0, v0, v36, v37
	v_max3_f32 v0, v0, v38, v39
	v_max3_f32 v0, v0, v40, v41
	v_max3_f32 v0, v0, v42, v43
	v_max3_f32 v0, v0, v44, v45
	v_max3_f32 v0, v0, v46, v47
	v_max3_f32 v0, v0, v16, v17
	v_max3_f32 v0, v0, v18, v19
	v_max3_f32 v0, v0, v20, v21
	v_max3_f32 v0, v0, v22, v23
	v_max3_f32 v0, v0, v24, v25
	v_max3_f32 v0, v0, v26, v27
	v_max3_f32 v0, v0, v28, v29
	v_max3_f32 v0, v0, v30, v31
	v_mov_b32_e32 v1, v0
	s_nop 1
	v_permlane32_swap_b32_e32 v0, v1
	v_max_f32_e32 v1, v1, v1
	v_max_f32_e32 v0, v0, v0
	v_max_f32_e32 v0, v0, v1
	v_add_f32_e32 v1, 0x7149f2ca, v0
	v_cmp_ge_f32_e32 vcc, s14, v1
	s_cmp_eq_u64 vcc, exec
	s_cselect_b64 vcc, -1, 0
	s_add_u32 s2, s20, 0x610000
	s_addc_u32 s3, s21, 0
	s_add_u32 s22, s20, 0xa10000
	s_addc_u32 s23, s21, 0
	v_max_f32_e32 v68, 0xf149f2ca, v0
	v_lshl_add_u64 v[0:1], s[22:23], 0, v[132:133]
	v_lshl_add_u64 v[2:3], s[22:23], 0, v[134:135]
	v_lshl_add_u64 v[0:1], v[0:1], 0, v[188:189]
	v_lshl_add_u64 v[2:3], v[2:3], 0, v[188:189]
	global_load_dwordx4 v[48:51], v[0:1], off
	global_load_dwordx4 v[52:55], v[2:3], off
	v_lshl_add_u64 v[0:1], s[2:3], 0, v[132:133]
	v_lshl_add_u64 v[2:3], s[2:3], 0, v[134:135]
	s_add_u32 s2, s20, 0x620000
	v_lshl_add_u64 v[0:1], v[0:1], 0, v[188:189]
	s_addc_u32 s3, s21, 0
	v_lshl_add_u64 v[2:3], v[2:3], 0, v[188:189]
	global_load_dwordx4 v[56:59], v[0:1], off
	global_load_dwordx4 v[60:63], v[2:3], off
	s_add_u32 s20, s20, 0xa20000
	v_lshl_add_u64 v[0:1], s[2:3], 0, v[134:135]
	s_addc_u32 s21, s21, 0
	v_lshl_add_u64 v[0:1], v[0:1], 0, v[188:189]
	v_lshl_add_u64 v[2:3], s[2:3], 0, v[132:133]
	v_lshl_add_u64 v[2:3], v[2:3], 0, v[188:189]
	global_load_dwordx4 v[140:143], v[0:1], off
	global_load_dwordx4 v[136:139], v[2:3], off
	v_lshl_add_u64 v[0:1], s[20:21], 0, v[134:135]
	v_lshl_add_u64 v[0:1], v[0:1], 0, v[188:189]
	v_lshl_add_u64 v[2:3], s[20:21], 0, v[132:133]
	v_lshl_add_u64 v[2:3], v[2:3], 0, v[188:189]
	global_load_dwordx4 v[132:135], v[0:1], off
	global_load_dwordx4 v[128:131], v[2:3], off
	v_sub_f32_e32 v0, 0xf149f2ca, v68
	v_mul_f32_e32 v0, 0x3e0293ee, v0
	v_exp_f32_e32 v70, v0
	v_cndmask_b32_e32 v168, v68, v246, vcc
	v_mul_f32_e32 v68, 0xbe0293ee, v168
	v_fmamk_f32 v32, v32, 0x3e0293ee, v68
	v_cndmask_b32_e64 v212, v70, 1.0, vcc
	v_mov_b32_e32 v70, v68
	v_fmamk_f32 v33, v33, 0x3e0293ee, v68
	v_fmamk_f32 v34, v34, 0x3e0293ee, v68
	v_fmamk_f32 v35, v35, 0x3e0293ee, v68
	v_fmamk_f32 v36, v36, 0x3e0293ee, v68
	v_fmamk_f32 v37, v37, 0x3e0293ee, v68
	v_fmamk_f32 v38, v38, 0x3e0293ee, v68
	v_fmamk_f32 v39, v39, 0x3e0293ee, v68
	v_fmamk_f32 v40, v40, 0x3e0293ee, v68
	v_fmamk_f32 v41, v41, 0x3e0293ee, v68
	v_fmamk_f32 v42, v42, 0x3e0293ee, v68
	v_fmamk_f32 v43, v43, 0x3e0293ee, v68
	v_fmamk_f32 v44, v44, 0x3e0293ee, v68
	v_fmamk_f32 v45, v45, 0x3e0293ee, v68
	v_fmamk_f32 v46, v46, 0x3e0293ee, v68
	v_fmac_f32_e32 v70, 0x3e0293ee, v47
	s_mov_b32 s20, s17
	s_mov_b32 s21, s17
	s_mov_b32 s22, s17
	s_mov_b32 s23, s17
	v_mov_b64_e32 v[0:1], s[16:17]
	v_exp_f32_e32 v216, v32
	v_exp_f32_e32 v230, v33
	v_exp_f32_e32 v174, v34
	v_exp_f32_e32 v219, v35
	v_exp_f32_e32 v173, v36
	v_exp_f32_e32 v175, v37
	v_exp_f32_e32 v163, v38
	v_exp_f32_e32 v172, v39
	v_exp_f32_e32 v164, v40
	v_exp_f32_e32 v171, v41
	v_exp_f32_e32 v165, v42
	v_exp_f32_e32 v170, v43
	v_exp_f32_e32 v166, v44
	v_exp_f32_e32 v169, v45
	v_exp_f32_e32 v145, v46
	v_exp_f32_e32 v167, v70
	v_mov_b64_e32 v[14:15], s[30:31]
	s_waitcnt vmcnt(4)
	v_mov_b64_e32 v[2:3], s[18:19]
	v_mov_b64_e32 v[4:5], s[20:21]
	v_mov_b64_e32 v[6:7], s[22:23]
	v_mov_b64_e32 v[8:9], s[24:25]
	v_mov_b64_e32 v[10:11], s[26:27]
	v_mov_b64_e32 v[12:13], s[28:29]
	v_pk_fma_f32 v[152:153], v[30:31], s[88:89], v[68:69] op_sel_hi:[1,0,0]
	v_pk_fma_f32 v[154:155], v[28:29], s[88:89], v[68:69] op_sel_hi:[1,0,0]
	v_pk_fma_f32 v[160:161], v[26:27], s[88:89], v[68:69] op_sel_hi:[1,0,0]
	v_pk_fma_f32 v[146:147], v[24:25], s[88:89], v[68:69] op_sel_hi:[1,0,0]
	v_pk_fma_f32 v[148:149], v[22:23], s[88:89], v[68:69] op_sel_hi:[1,0,0]
	v_pk_fma_f32 v[150:151], v[20:21], s[88:89], v[68:69] op_sel_hi:[1,0,0]
	v_pk_fma_f32 v[156:157], v[18:19], s[88:89], v[68:69] op_sel_hi:[1,0,0]
	v_pk_fma_f32 v[158:159], v[16:17], s[88:89], v[68:69] op_sel_hi:[1,0,0]
	s_waitcnt vmcnt(7)
	ds_write_b128 v200, v[48:51] offset:16384
	s_waitcnt vmcnt(6)
	ds_write_b128 v201, v[52:55] offset:16384
	s_waitcnt vmcnt(5)
	ds_write_b128 v202, v[56:59] offset:49152
	s_waitcnt vmcnt(4)
	ds_write_b128 v203, v[60:63] offset:49152
	s_addk_i32 s4, 0x4000
	v_mov_b64_e32 v[62:63], v[14:15]
	v_mov_b64_e32 v[46:47], v[14:15]
	v_mov_b64_e32 v[30:31], v[14:15]
	v_cmp_gt_u32_e64 s[2:3], 32, v196
	v_lshl_add_u32 v189, v227, 2, v191
	v_add_u32_e32 v198, s4, v69
	v_mov_b64_e32 v[60:61], v[12:13]
	v_mov_b64_e32 v[58:59], v[10:11]
	v_mov_b64_e32 v[56:57], v[8:9]
	v_mov_b64_e32 v[54:55], v[6:7]
	v_mov_b64_e32 v[52:53], v[4:5]
	v_mov_b64_e32 v[50:51], v[2:3]
	v_mov_b64_e32 v[48:49], v[0:1]
	v_mov_b64_e32 v[44:45], v[12:13]
	v_mov_b64_e32 v[42:43], v[10:11]
	v_mov_b64_e32 v[40:41], v[8:9]
	v_mov_b64_e32 v[38:39], v[6:7]
	v_mov_b64_e32 v[36:37], v[4:5]
	v_mov_b64_e32 v[34:35], v[2:3]
	v_mov_b64_e32 v[32:33], v[0:1]
	v_mov_b64_e32 v[28:29], v[12:13]
	v_mov_b64_e32 v[26:27], v[10:11]
	v_mov_b64_e32 v[24:25], v[8:9]
	v_mov_b64_e32 v[22:23], v[6:7]
	v_mov_b64_e32 v[20:21], v[4:5]
	v_mov_b64_e32 v[18:19], v[2:3]
	v_mov_b64_e32 v[16:17], v[0:1]
	v_add_u32_e32 v222, v192, v176
	v_add_u32_e32 v243, v194, v176
	s_waitcnt lgkmcnt(0)
.Lhead709:
	s_barrier
.LBB0_709:
	s_add_i32 s20, s85, -3
	ds_read_b128 v[64:67], v204 offset:49152
	ds_read_b128 v[68:71], v204 offset:57344
	ds_read_b128 v[178:181], v207 offset:49152
	ds_read_b128 v[182:185], v207 offset:57344
	v_exp_f32_e32 v144, v158
	v_exp_f32_e32 v158, v159
	s_waitcnt lgkmcnt(3)
	v_mfma_f32_32x32x16_bf16 v[80:95], v[64:67], v[124:127], 0
	v_exp_f32_e32 v159, v160
	v_add_f32_e32 v160, 0, v216
	v_add_f32_e32 v160, v230, v160
	v_add_f32_e32 v160, v174, v160
	v_add_f32_e32 v160, v219, v160
	v_add_f32_e32 v160, v173, v160
	v_add_f32_e32 v160, v175, v160
	s_waitcnt lgkmcnt(2)
	v_mfma_f32_32x32x16_bf16 v[64:79], v[68:71], v[124:127], 0
	v_add_f32_e32 v160, v163, v160
	v_add_f32_e32 v160, v172, v160
	v_add_f32_e32 v160, v164, v160
	v_add_f32_e32 v160, v171, v160
	v_add_f32_e32 v160, v165, v160
	v_add_f32_e32 v160, v170, v160
	v_add_f32_e32 v160, v166, v160
	s_waitcnt lgkmcnt(1)
	v_mfma_f32_32x32x16_bf16 v[80:95], v[178:181], v[120:123], v[80:95]
	v_add_f32_e32 v160, v169, v160
	v_exp_f32_e32 v156, v156
	v_add_f32_e32 v160, v145, v160
	v_exp_f32_e32 v157, v157
	v_add_f32_e32 v160, v167, v160
	v_exp_f32_e32 v150, v150
	v_add_f32_e32 v160, v144, v160
	s_waitcnt lgkmcnt(0)
	v_mfma_f32_32x32x16_bf16 v[64:79], v[182:185], v[120:123], v[64:79]
	ds_read_b128 v[178:181], v209 offset:49152
	ds_read_b128 v[182:185], v209 offset:57344
	v_exp_f32_e32 v151, v151
	v_add_f32_e32 v160, v158, v160
	v_exp_f32_e32 v148, v148
	v_add_f32_e32 v160, v156, v160
	v_exp_f32_e32 v149, v149
	v_add_f32_e32 v160, v157, v160
	s_waitcnt lgkmcnt(1)
	v_mfma_f32_32x32x16_bf16 v[80:95], v[178:181], v[116:119], v[80:95]
	v_exp_f32_e32 v146, v146
	v_add_f32_e32 v160, v150, v160
	v_exp_f32_e32 v147, v147
	v_add_f32_e32 v160, v151, v160
	v_add_f32_e32 v160, v148, v160
	v_add_f32_e32 v160, v149, v160
	v_exp_f32_e32 v154, v154
	s_waitcnt lgkmcnt(0)
	v_mfma_f32_32x32x16_bf16 v[64:79], v[182:185], v[116:119], v[64:79]
	ds_read_b128 v[178:181], v205 offset:49152
	ds_read_b128 v[182:185], v205 offset:57344
	v_add_f32_e32 v160, v146, v160
	v_exp_f32_e32 v155, v155
	v_add_f32_e32 v160, v147, v160
	v_exp_f32_e32 v152, v152
	v_add_f32_e32 v160, v159, v160
	v_exp_f32_e32 v153, v153
	s_waitcnt lgkmcnt(1)
	v_mfma_f32_32x32x16_bf16 v[80:95], v[178:181], v[112:115], v[80:95]
	s_waitcnt lgkmcnt(0)
	v_mfma_f32_32x32x16_bf16 v[64:79], v[182:185], v[112:115], v[64:79]
	ds_read_b128 v[178:181], v206 offset:49152
	ds_read_b128 v[182:185], v206 offset:57344
	s_waitcnt lgkmcnt(1)
	v_mfma_f32_32x32x16_bf16 v[80:95], v[178:181], v[108:111], v[80:95]
	s_waitcnt lgkmcnt(0)
	v_mfma_f32_32x32x16_bf16 v[64:79], v[182:185], v[108:111], v[64:79]
	ds_read_b128 v[178:181], v208 offset:49152
	ds_read_b128 v[182:185], v208 offset:57344
	s_waitcnt lgkmcnt(1)
	v_mfma_f32_32x32x16_bf16 v[80:95], v[178:181], v[104:107], v[80:95]
	s_waitcnt lgkmcnt(0)
	v_mfma_f32_32x32x16_bf16 v[64:79], v[182:185], v[104:107], v[64:79]
	ds_read_b128 v[178:181], v210 offset:49152
	ds_read_b128 v[182:185], v210 offset:57344
	s_waitcnt lgkmcnt(1)
	v_mfma_f32_32x32x16_bf16 v[80:95], v[178:181], v[100:103], v[80:95]
	s_waitcnt lgkmcnt(0)
	v_mfma_f32_32x32x16_bf16 v[64:79], v[182:185], v[100:103], v[64:79]
	ds_read_b128 v[178:181], v211 offset:49152
	ds_read_b128 v[182:185], v211 offset:57344
	s_waitcnt lgkmcnt(1)
	v_mfma_f32_32x32x16_bf16 v[80:95], v[178:181], v[96:99], v[80:95]
	v_exp_f32_e32 v179, v161
	s_nop 0
	v_add_f32_e32 v160, v179, v160
	v_add_f32_e32 v160, v154, v160
	v_add_f32_e32 v160, v155, v160
	s_waitcnt lgkmcnt(0)
	v_mfma_f32_32x32x16_bf16 v[64:79], v[182:185], v[96:99], v[64:79]
	v_add_f32_e32 v160, v152, v160
	v_add_f32_e32 v213, v153, v160
	v_mov_b32_e32 v214, v213
	v_cvt_pk_bf16_f32 v160, v216, v230
	v_cvt_pk_bf16_f32 v161, v174, v219
	v_cvt_pk_bf16_f32 v162, v173, v175
	s_nop 1
	v_permlane32_swap_b32_e32 v213, v214
	v_cvt_pk_bf16_f32 v163, v163, v172
	v_permlane32_swap_b32_e32 v160, v162
	v_cvt_pk_bf16_f32 v164, v164, v171
	v_cvt_pk_bf16_f32 v165, v165, v170
	v_cvt_pk_bf16_f32 v166, v166, v169
	v_cvt_pk_bf16_f32 v167, v145, v167
	v_cvt_pk_bf16_f32 v170, v144, v158
	v_cvt_pk_bf16_f32 v171, v156, v157
	v_cvt_pk_bf16_f32 v172, v150, v151
	v_cvt_pk_bf16_f32 v173, v148, v149
	v_cvt_pk_bf16_f32 v178, v146, v147
	v_cvt_pk_bf16_f32 v179, v159, v179
	v_cvt_pk_bf16_f32 v180, v154, v155
	v_cvt_pk_bf16_f32 v181, v152, v153
	v_permlane32_swap_b32_e32 v161, v163
	v_permlane32_swap_b32_e32 v164, v166
	v_permlane32_swap_b32_e32 v165, v167
	v_permlane32_swap_b32_e32 v170, v172
	v_permlane32_swap_b32_e32 v171, v173
	v_permlane32_swap_b32_e32 v178, v180
	v_permlane32_swap_b32_e32 v179, v181
	s_cmp_lt_u32 s20, 6
	s_cselect_b64 s[4:5], -1, 0
	s_and_b64 s[18:19], s[4:5], exec
	s_cselect_b32 s16, 0, -8
	s_add_i32 s16, s16, s85
	s_add_i32 s16, s16, -1
	s_and_b64 s[4:5], s[4:5], exec
	s_cselect_b32 s19, s49, s43
	s_cselect_b32 s18, s48, s36
	s_cselect_b32 s21, s57, s52
	s_cselect_b32 s22, s56, s44
	s_lshl_b64 s[4:5], s[16:17], 16
	s_add_u32 s18, s18, s4
	s_addc_u32 s19, s19, s5
	s_add_u32 s4, s22, s4
	s_addc_u32 s5, s21, s5
	global_load_dwordx4 v[144:147], v222, s[4:5]
	global_load_dwordx4 v[148:151], v243, s[4:5]
	global_load_dwordx4 v[152:155], v222, s[18:19]
	global_load_dwordx4 v[156:159], v243, s[18:19]
	ds_read_b64_tr_b16 v[182:183], v199 offset:0
	ds_read_b64_tr_b16 v[184:185], v199 offset:0x800
	ds_read_b64_tr_b16 v[216:217], v199 offset:0x1000
	ds_read_b64_tr_b16 v[218:219], v199 offset:0x1800
	ds_read_b64_tr_b16 v[230:231], v199 offset:0x2000
	ds_read_b64_tr_b16 v[232:233], v199 offset:0x2800
	ds_read_b64_tr_b16 v[234:235], v199 offset:0x3000
	ds_read_b64_tr_b16 v[236:237], v199 offset:0x3800
	s_waitcnt lgkmcnt(0)
	s_nop 0
	v_mfma_f32_32x32x16_bf16 v[0:15], v[160:163], v[182:185], v[0:15]
	ds_read_b64_tr_b16 v[182:183], v199 offset:0x200
	ds_read_b64_tr_b16 v[184:185], v199 offset:0xa00
	v_mfma_f32_32x32x16_bf16 v[0:15], v[164:167], v[216:219], v[0:15]
	ds_read_b64_tr_b16 v[216:217], v199 offset:0x1200
	ds_read_b64_tr_b16 v[218:219], v199 offset:0x1a00
	v_mfma_f32_32x32x16_bf16 v[0:15], v[170:173], v[230:233], v[0:15]
	ds_read_b64_tr_b16 v[230:231], v199 offset:0x2200
	ds_read_b64_tr_b16 v[232:233], v199 offset:0x2a00
	v_mfma_f32_32x32x16_bf16 v[0:15], v[178:181], v[234:237], v[0:15]
	ds_read_b64_tr_b16 v[234:235], v199 offset:0x3200
	ds_read_b64_tr_b16 v[236:237], v199 offset:0x3a00
	s_waitcnt lgkmcnt(0)
	v_mfma_f32_32x32x16_bf16 v[48:63], v[160:163], v[182:185], v[48:63]
	ds_read_b64_tr_b16 v[182:183], v199 offset:0x400
	ds_read_b64_tr_b16 v[184:185], v199 offset:0xc00
	v_mfma_f32_32x32x16_bf16 v[48:63], v[164:167], v[216:219], v[48:63]
	ds_read_b64_tr_b16 v[216:217], v199 offset:0x1400
	ds_read_b64_tr_b16 v[218:219], v199 offset:0x1c00
	v_mfma_f32_32x32x16_bf16 v[48:63], v[170:173], v[230:233], v[48:63]
	ds_read_b64_tr_b16 v[230:231], v199 offset:0x2400
	ds_read_b64_tr_b16 v[232:233], v199 offset:0x2c00
	v_mfma_f32_32x32x16_bf16 v[48:63], v[178:181], v[234:237], v[48:63]
	ds_read_b64_tr_b16 v[234:235], v199 offset:0x3400
	ds_read_b64_tr_b16 v[236:237], v199 offset:0x3c00
	s_waitcnt lgkmcnt(0)
	v_mfma_f32_32x32x16_bf16 v[32:47], v[160:163], v[182:185], v[32:47]
	ds_read_b64_tr_b16 v[182:183], v199 offset:0x600
	ds_read_b64_tr_b16 v[184:185], v199 offset:0xe00
	v_mfma_f32_32x32x16_bf16 v[32:47], v[164:167], v[216:219], v[32:47]
	ds_read_b64_tr_b16 v[216:217], v199 offset:0x1600
	ds_read_b64_tr_b16 v[218:219], v199 offset:0x1e00
	v_mfma_f32_32x32x16_bf16 v[32:47], v[170:173], v[230:233], v[32:47]
	ds_read_b64_tr_b16 v[230:231], v199 offset:0x2600
	ds_read_b64_tr_b16 v[232:233], v199 offset:0x2e00
	v_mfma_f32_32x32x16_bf16 v[32:47], v[178:181], v[234:237], v[32:47]
	ds_read_b64_tr_b16 v[234:235], v199 offset:0x3600
	ds_read_b64_tr_b16 v[236:237], v199 offset:0x3e00
	s_waitcnt lgkmcnt(0)
	v_mfma_f32_32x32x16_bf16 v[16:31], v[160:163], v[182:185], v[16:31]
	v_max_f32_e32 v160, v81, v81
	v_max_f32_e32 v161, v80, v80
	v_max_f32_e32 v160, v161, v160
	v_max3_f32 v160, v160, v82, v83
	v_max3_f32 v160, v160, v84, v85
	v_max3_f32 v160, v160, v86, v87
	v_max3_f32 v160, v160, v88, v89
	v_max3_f32 v160, v160, v90, v91
	v_max3_f32 v160, v160, v92, v93
	v_mfma_f32_32x32x16_bf16 v[16:31], v[164:167], v[216:219], v[16:31]
	v_max3_f32 v160, v160, v94, v95
	v_max3_f32 v160, v160, v64, v65
	v_max3_f32 v160, v160, v66, v67
	v_max3_f32 v160, v160, v68, v69
	v_max3_f32 v160, v160, v70, v71
	v_max3_f32 v160, v160, v72, v73
	v_max3_f32 v160, v160, v74, v75
	v_max3_f32 v160, v160, v76, v77
	v_mfma_f32_32x32x16_bf16 v[16:31], v[170:173], v[230:233], v[16:31]
	v_max3_f32 v160, v160, v78, v79
	v_mov_b32_e32 v161, v160
	s_nop 1
	v_permlane32_swap_b32_e32 v160, v161
	v_max_f32_e32 v161, v161, v161
	v_max_f32_e32 v160, v160, v160
	v_max_f32_e32 v160, v160, v161
	v_sub_f32_e32 v161, v160, v168
	v_cmp_ge_f32_e32 vcc, s14, v161
	v_max_f32_e32 v161, v168, v168
	v_max_f32_e32 v160, v161, v160
	v_mfma_f32_32x32x16_bf16 v[16:31], v[178:181], v[234:237], v[16:31]
	v_sub_f32_e32 v161, v168, v160
	v_mul_f32_e32 v161, 0x3e0293ee, v161
	v_exp_f32_e32 v161, v161
	s_cmp_eq_u64 vcc, exec
	s_cselect_b64 s[4:5], -1, 0
	s_barrier
	s_waitcnt vmcnt(4)
	v_cndmask_b32_e64 v215, v161, 1.0, s[4:5]
	v_cmp_gt_f32_e32 vcc, 1.0, v215
	s_waitcnt vmcnt(4)
	ds_write_b128 v200, v[128:131]
	ds_write_b128 v201, v[132:135]
	ds_write_b128 v202, v[136:139] offset:32768
	ds_write_b128 v203, v[140:143] offset:32768
	s_cbranch_vccz .LBB0_713
	s_and_saveexec_b64 s[18:19], s[2:3]
	ds_write_b32 v189, v215 offset:128
	s_or_b64 exec, exec, s[18:19]
	s_waitcnt lgkmcnt(0)
	v_add_u32_e32 v161, v191, v190
	ds_read_b128 v[162:165], v161 offset:224
	ds_read_b128 v[170:173], v161 offset:192
	ds_read_b128 v[178:181], v161 offset:160
	ds_read_b128 v[182:185], v161 offset:128
	s_waitcnt lgkmcnt(3)
	v_pk_mul_f32 v[12:13], v[12:13], v[162:163]
	s_waitcnt lgkmcnt(2)
	v_pk_mul_f32 v[8:9], v[8:9], v[170:171]
	s_waitcnt lgkmcnt(1)
	v_pk_mul_f32 v[4:5], v[4:5], v[178:179]
	v_pk_mul_f32 v[14:15], v[14:15], v[164:165]
	v_pk_mul_f32 v[10:11], v[10:11], v[172:173]
	v_pk_mul_f32 v[6:7], v[6:7], v[180:181]
	s_waitcnt lgkmcnt(0)
	v_pk_mul_f32 v[2:3], v[2:3], v[184:185]
	v_pk_mul_f32 v[0:1], v[0:1], v[182:183]
	v_pk_mul_f32 v[60:61], v[60:61], v[162:163]
	v_pk_mul_f32 v[56:57], v[56:57], v[170:171]
	v_pk_mul_f32 v[52:53], v[52:53], v[178:179]
	v_pk_mul_f32 v[62:63], v[62:63], v[164:165]
	v_pk_mul_f32 v[58:59], v[58:59], v[172:173]
	v_pk_mul_f32 v[54:55], v[54:55], v[180:181]
	v_pk_mul_f32 v[50:51], v[50:51], v[184:185]
	v_pk_mul_f32 v[48:49], v[48:49], v[182:183]
	v_pk_mul_f32 v[44:45], v[44:45], v[162:163]
	v_pk_mul_f32 v[40:41], v[40:41], v[170:171]
	v_pk_mul_f32 v[36:37], v[36:37], v[178:179]
	v_pk_mul_f32 v[46:47], v[46:47], v[164:165]
	v_pk_mul_f32 v[42:43], v[42:43], v[172:173]
	v_pk_mul_f32 v[38:39], v[38:39], v[180:181]
	v_pk_mul_f32 v[34:35], v[34:35], v[184:185]
	v_pk_mul_f32 v[32:33], v[32:33], v[182:183]
	v_pk_mul_f32 v[28:29], v[28:29], v[162:163]
	v_pk_mul_f32 v[24:25], v[24:25], v[170:171]
	v_pk_mul_f32 v[20:21], v[20:21], v[178:179]
	v_pk_mul_f32 v[30:31], v[30:31], v[164:165]
	v_pk_mul_f32 v[26:27], v[26:27], v[172:173]
	v_pk_mul_f32 v[22:23], v[22:23], v[180:181]
	v_pk_mul_f32 v[18:19], v[18:19], v[184:185]
	v_pk_mul_f32 v[16:17], v[16:17], v[182:183]

.LBB0_719:
	v_cndmask_b32_e64 v168, v160, v216, s[4:5]
	v_mul_f32_e32 v144, 0xbe0293ee, v168
	v_fmamk_f32 v94, v94, 0x3e0293ee, v144
	v_mov_b32_e32 v152, v144
	v_fmamk_f32 v80, v80, 0x3e0293ee, v144
	v_fmamk_f32 v81, v81, 0x3e0293ee, v144
	v_fmamk_f32 v82, v82, 0x3e0293ee, v144
	v_fmamk_f32 v83, v83, 0x3e0293ee, v144
	v_fmamk_f32 v84, v84, 0x3e0293ee, v144
	v_fmamk_f32 v85, v85, 0x3e0293ee, v144
	v_fmamk_f32 v86, v86, 0x3e0293ee, v144
	v_fmamk_f32 v87, v87, 0x3e0293ee, v144
	v_fmamk_f32 v88, v88, 0x3e0293ee, v144
	v_fmamk_f32 v89, v89, 0x3e0293ee, v144
	v_fmamk_f32 v90, v90, 0x3e0293ee, v144
	v_fmamk_f32 v91, v91, 0x3e0293ee, v144
	v_fmamk_f32 v92, v92, 0x3e0293ee, v144
	v_fmamk_f32 v93, v93, 0x3e0293ee, v144
	v_fmac_f32_e32 v152, 0x3e0293ee, v95
	v_pk_fma_f32 v[158:159], v[64:65], s[88:89], v[144:145] op_sel_hi:[1,0,0]
	v_pk_fma_f32 v[156:157], v[66:67], s[88:89], v[144:145] op_sel_hi:[1,0,0]
	v_pk_fma_f32 v[150:151], v[68:69], s[88:89], v[144:145] op_sel_hi:[1,0,0]
	v_pk_fma_f32 v[148:149], v[70:71], s[88:89], v[144:145] op_sel_hi:[1,0,0]
	v_pk_fma_f32 v[146:147], v[72:73], s[88:89], v[144:145] op_sel_hi:[1,0,0]
	v_exp_f32_e32 v145, v94
	v_exp_f32_e32 v216, v80
	v_exp_f32_e32 v230, v81
	v_exp_f32_e32 v174, v82
	v_exp_f32_e32 v219, v83
	v_exp_f32_e32 v173, v84
	v_exp_f32_e32 v175, v85
	v_exp_f32_e32 v163, v86
	v_exp_f32_e32 v172, v87
	v_exp_f32_e32 v164, v88
	v_exp_f32_e32 v171, v89
	v_exp_f32_e32 v165, v90
	v_exp_f32_e32 v170, v91
	v_exp_f32_e32 v166, v92
	v_exp_f32_e32 v169, v93
	v_exp_f32_e32 v167, v152
	v_add_f32_e32 v64, v213, v214
	v_fmac_f32_e32 v64, v212, v197
	v_add_f32_e32 v197, v217, v218
	s_add_i32 s85, s85, 2
	v_pk_fma_f32 v[160:161], v[74:75], s[88:89], v[144:145] op_sel_hi:[1,0,0]
	v_pk_fma_f32 v[154:155], v[76:77], s[88:89], v[144:145] op_sel_hi:[1,0,0]
	v_pk_fma_f32 v[152:153], v[78:79], s[88:89], v[144:145] op_sel_hi:[1,0,0]
	v_fmac_f32_e32 v197, v64, v215
	s_cmpk_gt_u32 s20, 0x44
	s_waitcnt lgkmcnt(0)
	s_cbranch_scc1 .Lexit709
	v_mov_b32_e32 v212, v162
	s_branch .Lhead709
.Lexit709:
	s_barrier
.LBB0_721:
	ds_read_b128 v[64:67], v204 offset:49152
	ds_read_b128 v[68:71], v204 offset:57344
	s_waitcnt lgkmcnt(1)
	v_mfma_f32_32x32x16_bf16 v[80:95], v[64:67], v[124:127], 0
	s_waitcnt lgkmcnt(0)
	v_mfma_f32_32x32x16_bf16 v[64:79], v[68:71], v[124:127], 0
	ds_read_b128 v[124:127], v207 offset:49152
	ds_read_b128 v[128:131], v207 offset:57344
	s_waitcnt lgkmcnt(1)
	v_mfma_f32_32x32x16_bf16 v[80:95], v[124:127], v[120:123], v[80:95]
	s_waitcnt lgkmcnt(0)
	v_mfma_f32_32x32x16_bf16 v[64:79], v[128:131], v[120:123], v[64:79]
	ds_read_b128 v[120:123], v209 offset:49152
	ds_read_b128 v[124:127], v209 offset:57344
	s_waitcnt lgkmcnt(1)
	v_mfma_f32_32x32x16_bf16 v[80:95], v[120:123], v[116:119], v[80:95]
	s_waitcnt lgkmcnt(0)
	v_mfma_f32_32x32x16_bf16 v[64:79], v[124:127], v[116:119], v[64:79]
	ds_read_b128 v[116:119], v205 offset:49152
	ds_read_b128 v[120:123], v205 offset:57344
	s_waitcnt lgkmcnt(1)
	v_mfma_f32_32x32x16_bf16 v[80:95], v[116:119], v[112:115], v[80:95]
	s_waitcnt lgkmcnt(0)
	v_mfma_f32_32x32x16_bf16 v[64:79], v[120:123], v[112:115], v[64:79]
	ds_read_b128 v[112:115], v206 offset:49152
	ds_read_b128 v[116:119], v206 offset:57344
	v_exp_f32_e32 v120, v152
	v_exp_f32_e32 v121, v153
	s_waitcnt lgkmcnt(1)
	v_mfma_f32_32x32x16_bf16 v[80:95], v[112:115], v[108:111], v[80:95]
	s_waitcnt lgkmcnt(0)
	v_mfma_f32_32x32x16_bf16 v[64:79], v[116:119], v[108:111], v[64:79]
	ds_read_b128 v[108:111], v208 offset:49152
	ds_read_b128 v[112:115], v208 offset:57344
	v_exp_f32_e32 v116, v160
	v_exp_f32_e32 v117, v161
	v_exp_f32_e32 v118, v154
	v_exp_f32_e32 v119, v155
	s_waitcnt lgkmcnt(1)
	v_mfma_f32_32x32x16_bf16 v[80:95], v[108:111], v[104:107], v[80:95]
	s_waitcnt lgkmcnt(0)
	v_mfma_f32_32x32x16_bf16 v[64:79], v[112:115], v[104:107], v[64:79]
	ds_read_b128 v[104:107], v210 offset:49152
	ds_read_b128 v[108:111], v210 offset:57344
	v_exp_f32_e32 v112, v148
	v_exp_f32_e32 v113, v149
	v_exp_f32_e32 v114, v146
	v_exp_f32_e32 v115, v147
	s_waitcnt lgkmcnt(1)
	v_mfma_f32_32x32x16_bf16 v[80:95], v[104:107], v[100:103], v[80:95]
	s_waitcnt lgkmcnt(0)
	v_mfma_f32_32x32x16_bf16 v[64:79], v[108:111], v[100:103], v[64:79]
	ds_read_b128 v[100:103], v211 offset:49152
	ds_read_b128 v[104:107], v211 offset:57344
	v_exp_f32_e32 v108, v156
	v_exp_f32_e32 v109, v157
	v_exp_f32_e32 v110, v150
	v_exp_f32_e32 v111, v151
	s_waitcnt lgkmcnt(1)
	v_mfma_f32_32x32x16_bf16 v[80:95], v[100:103], v[96:99], v[80:95]
	s_waitcnt lgkmcnt(0)
	v_mfma_f32_32x32x16_bf16 v[64:79], v[104:107], v[96:99], v[64:79]
	v_add_f32_e32 v96, 0, v216
	v_add_f32_e32 v96, v230, v96
	v_add_f32_e32 v96, v174, v96
	v_add_f32_e32 v96, v219, v96
	v_add_f32_e32 v96, v173, v96
	v_add_f32_e32 v96, v175, v96
	v_add_f32_e32 v96, v163, v96
	v_add_f32_e32 v96, v172, v96
	v_add_f32_e32 v96, v164, v96
	v_add_f32_e32 v96, v171, v96
	v_add_f32_e32 v96, v165, v96
	v_add_f32_e32 v96, v170, v96
	v_exp_f32_e32 v106, v158
	v_add_f32_e32 v96, v166, v96
	v_exp_f32_e32 v107, v159
	v_add_f32_e32 v96, v169, v96
	v_add_f32_e32 v96, v145, v96
	v_add_f32_e32 v96, v167, v96
	v_add_f32_e32 v96, v106, v96
	v_add_f32_e32 v96, v107, v96
	v_add_f32_e32 v96, v108, v96
	v_add_f32_e32 v96, v109, v96
	v_add_f32_e32 v96, v110, v96
	v_add_f32_e32 v96, v111, v96
	v_add_f32_e32 v96, v112, v96
	v_add_f32_e32 v96, v113, v96
	v_add_f32_e32 v96, v114, v96
	v_add_f32_e32 v96, v115, v96
	v_add_f32_e32 v96, v116, v96
	v_add_f32_e32 v96, v117, v96
	v_add_f32_e32 v96, v118, v96
	v_add_f32_e32 v96, v119, v96
	v_add_f32_e32 v96, v120, v96
	v_add_f32_e32 v96, v121, v96
	v_mov_b32_e32 v97, v96
	v_cvt_pk_bf16_f32 v98, v216, v230
	v_cvt_pk_bf16_f32 v99, v174, v219
	v_cvt_pk_bf16_f32 v100, v173, v175
	v_cvt_pk_bf16_f32 v101, v163, v172
	s_nop 1
	v_permlane32_swap_b32_e32 v96, v97
	v_permlane32_swap_b32_e32 v98, v100
	v_permlane32_swap_b32_e32 v99, v101
	v_cvt_pk_bf16_f32 v102, v164, v171
	v_cvt_pk_bf16_f32 v103, v165, v170
	v_cvt_pk_bf16_f32 v104, v166, v169
	v_cvt_pk_bf16_f32 v105, v145, v167
	v_cvt_pk_bf16_f32 v106, v106, v107
	v_cvt_pk_bf16_f32 v107, v108, v109
	v_cvt_pk_bf16_f32 v108, v110, v111
	v_cvt_pk_bf16_f32 v109, v112, v113
	v_cvt_pk_bf16_f32 v110, v114, v115
	v_cvt_pk_bf16_f32 v111, v116, v117
	v_cvt_pk_bf16_f32 v112, v118, v119
	v_cvt_pk_bf16_f32 v113, v120, v121
	s_nop 0
	v_permlane32_swap_b32_e32 v102, v104
	v_permlane32_swap_b32_e32 v103, v105
	v_permlane32_swap_b32_e32 v106, v108
	v_permlane32_swap_b32_e32 v107, v109
	v_permlane32_swap_b32_e32 v110, v112
	v_permlane32_swap_b32_e32 v111, v113
	ds_read_b64_tr_b16 v[114:115], v199 offset:0
	ds_read_b64_tr_b16 v[116:117], v199 offset:0x800
	ds_read_b64_tr_b16 v[118:119], v199 offset:0x1000
	ds_read_b64_tr_b16 v[120:121], v199 offset:0x1800
	ds_read_b64_tr_b16 v[122:123], v199 offset:0x2000
	ds_read_b64_tr_b16 v[124:125], v199 offset:0x2800
	ds_read_b64_tr_b16 v[126:127], v199 offset:0x3000
	ds_read_b64_tr_b16 v[128:129], v199 offset:0x3800
	s_waitcnt lgkmcnt(0)
	s_nop 0
	v_mfma_f32_32x32x16_bf16 v[0:15], v[98:101], v[114:117], v[0:15]
	ds_read_b64_tr_b16 v[114:115], v199 offset:0x200
	ds_read_b64_tr_b16 v[116:117], v199 offset:0xa00
	v_mfma_f32_32x32x16_bf16 v[0:15], v[102:105], v[118:121], v[0:15]
	ds_read_b64_tr_b16 v[118:119], v199 offset:0x1200
	ds_read_b64_tr_b16 v[120:121], v199 offset:0x1a00
	v_mfma_f32_32x32x16_bf16 v[0:15], v[106:109], v[122:125], v[0:15]
	ds_read_b64_tr_b16 v[122:123], v199 offset:0x2200
	ds_read_b64_tr_b16 v[124:125], v199 offset:0x2a00
	v_mfma_f32_32x32x16_bf16 v[0:15], v[110:113], v[126:129], v[0:15]
	ds_read_b64_tr_b16 v[126:127], v199 offset:0x3200
	ds_read_b64_tr_b16 v[128:129], v199 offset:0x3a00
	s_waitcnt lgkmcnt(0)
	v_mfma_f32_32x32x16_bf16 v[48:63], v[98:101], v[114:117], v[48:63]
	ds_read_b64_tr_b16 v[114:115], v199 offset:0x400
	ds_read_b64_tr_b16 v[116:117], v199 offset:0xc00
	v_mfma_f32_32x32x16_bf16 v[48:63], v[102:105], v[118:121], v[48:63]
	ds_read_b64_tr_b16 v[118:119], v199 offset:0x1400
	ds_read_b64_tr_b16 v[120:121], v199 offset:0x1c00
	v_mfma_f32_32x32x16_bf16 v[48:63], v[106:109], v[122:125], v[48:63]
	ds_read_b64_tr_b16 v[122:123], v199 offset:0x2400
	ds_read_b64_tr_b16 v[124:125], v199 offset:0x2c00
	v_mfma_f32_32x32x16_bf16 v[48:63], v[110:113], v[126:129], v[48:63]
	ds_read_b64_tr_b16 v[126:127], v199 offset:0x3400
	ds_read_b64_tr_b16 v[128:129], v199 offset:0x3c00
	s_waitcnt lgkmcnt(0)
	v_mfma_f32_32x32x16_bf16 v[32:47], v[98:101], v[114:117], v[32:47]
	ds_read_b64_tr_b16 v[114:115], v199 offset:0x600
	ds_read_b64_tr_b16 v[116:117], v199 offset:0xe00
	v_mfma_f32_32x32x16_bf16 v[32:47], v[102:105], v[118:121], v[32:47]
	ds_read_b64_tr_b16 v[118:119], v199 offset:0x1600
	ds_read_b64_tr_b16 v[120:121], v199 offset:0x1e00
	v_mfma_f32_32x32x16_bf16 v[32:47], v[106:109], v[122:125], v[32:47]
	ds_read_b64_tr_b16 v[122:123], v199 offset:0x2600
	ds_read_b64_tr_b16 v[124:125], v199 offset:0x2e00
	v_mfma_f32_32x32x16_bf16 v[32:47], v[110:113], v[126:129], v[32:47]
	ds_read_b64_tr_b16 v[126:127], v199 offset:0x3600
	ds_read_b64_tr_b16 v[128:129], v199 offset:0x3e00
	s_waitcnt lgkmcnt(0)
	v_mfma_f32_32x32x16_bf16 v[16:31], v[98:101], v[114:117], v[16:31]
	v_max_f32_e32 v98, v81, v81
	v_max_f32_e32 v99, v80, v80
	v_max_f32_e32 v98, v99, v98
	v_max3_f32 v98, v98, v82, v83
	v_max3_f32 v98, v98, v84, v85
	v_max3_f32 v98, v98, v86, v87
	v_max3_f32 v98, v98, v88, v89
	v_max3_f32 v98, v98, v90, v91
	v_max3_f32 v98, v98, v92, v93
	v_mfma_f32_32x32x16_bf16 v[16:31], v[102:105], v[118:121], v[16:31]
	v_max3_f32 v98, v98, v94, v95
	v_max3_f32 v98, v98, v64, v65
	v_max3_f32 v98, v98, v66, v67
	v_max3_f32 v98, v98, v68, v69
	v_max3_f32 v98, v98, v70, v71
	v_max3_f32 v98, v98, v72, v73
	v_max3_f32 v98, v98, v74, v75
	v_max3_f32 v98, v98, v76, v77
	v_mfma_f32_32x32x16_bf16 v[16:31], v[106:109], v[122:125], v[16:31]
	v_max3_f32 v98, v98, v78, v79
	v_mov_b32_e32 v99, v98
	s_nop 1
	v_permlane32_swap_b32_e32 v98, v99
	v_max_f32_e32 v99, v99, v99
	v_max_f32_e32 v98, v98, v98
	v_max_f32_e32 v98, v98, v99
	v_sub_f32_e32 v99, v98, v168
	v_cmp_ge_f32_e32 vcc, s14, v99
	v_max_f32_e32 v99, v168, v168
	v_max_f32_e32 v99, v99, v98
	v_mfma_f32_32x32x16_bf16 v[16:31], v[110:113], v[126:129], v[16:31]
	v_sub_f32_e32 v98, v168, v99
	v_mul_f32_e32 v98, 0x3e0293ee, v98
	v_exp_f32_e32 v98, v98
	s_cmp_eq_u64 vcc, exec
	s_cselect_b64 s[4:5], -1, 0
	v_cndmask_b32_e64 v98, v98, 1.0, s[4:5]
	v_cmp_gt_f32_e32 vcc, 1.0, v98
	s_barrier
	s_cbranch_vccz .LBB0_725
	s_and_saveexec_b64 s[18:19], s[2:3]
	ds_write_b32 v189, v98 offset:128
	s_or_b64 exec, exec, s[18:19]
	s_waitcnt lgkmcnt(0)
	v_add_u32_e32 v112, v191, v190
	ds_read_b128 v[100:103], v112 offset:224
	ds_read_b128 v[104:107], v112 offset:192
	ds_read_b128 v[108:111], v112 offset:160
	ds_read_b128 v[112:115], v112 offset:128
	s_waitcnt lgkmcnt(3)
	v_pk_mul_f32 v[12:13], v[12:13], v[100:101]
	s_waitcnt lgkmcnt(2)
	v_pk_mul_f32 v[8:9], v[8:9], v[104:105]
	s_waitcnt lgkmcnt(1)
	v_pk_mul_f32 v[4:5], v[4:5], v[108:109]
	v_pk_mul_f32 v[14:15], v[14:15], v[102:103]
	v_pk_mul_f32 v[10:11], v[10:11], v[106:107]
	v_pk_mul_f32 v[6:7], v[6:7], v[110:111]
	s_waitcnt lgkmcnt(0)
	v_pk_mul_f32 v[2:3], v[2:3], v[114:115]
	v_pk_mul_f32 v[0:1], v[0:1], v[112:113]
	v_pk_mul_f32 v[60:61], v[60:61], v[100:101]
	v_pk_mul_f32 v[56:57], v[56:57], v[104:105]
	v_pk_mul_f32 v[52:53], v[52:53], v[108:109]
	v_pk_mul_f32 v[62:63], v[62:63], v[102:103]
	v_pk_mul_f32 v[58:59], v[58:59], v[106:107]
	v_pk_mul_f32 v[54:55], v[54:55], v[110:111]
	v_pk_mul_f32 v[50:51], v[50:51], v[114:115]
	v_pk_mul_f32 v[48:49], v[48:49], v[112:113]
	v_pk_mul_f32 v[44:45], v[44:45], v[100:101]
	v_pk_mul_f32 v[40:41], v[40:41], v[104:105]
	v_pk_mul_f32 v[36:37], v[36:37], v[108:109]
	v_pk_mul_f32 v[46:47], v[46:47], v[102:103]
	v_pk_mul_f32 v[42:43], v[42:43], v[106:107]
	v_pk_mul_f32 v[38:39], v[38:39], v[110:111]
	v_pk_mul_f32 v[34:35], v[34:35], v[114:115]
	v_pk_mul_f32 v[32:33], v[32:33], v[112:113]
	v_pk_mul_f32 v[28:29], v[28:29], v[100:101]
	v_pk_mul_f32 v[24:25], v[24:25], v[104:105]
	v_pk_mul_f32 v[20:21], v[20:21], v[108:109]
	v_pk_mul_f32 v[30:31], v[30:31], v[102:103]
	v_pk_mul_f32 v[26:27], v[26:27], v[106:107]
	v_pk_mul_f32 v[22:23], v[22:23], v[110:111]
	v_pk_mul_f32 v[18:19], v[18:19], v[114:115]
	v_pk_mul_f32 v[16:17], v[16:17], v[112:113]
